# G3 K-loop: B1 fragments read last; leading half passes the load-segment barrier with the 4 B1 reads in flight, B1 awaited before the second MFMA block
# speedup vs baseline: 1.0080x; 1.0080x over previous
.Lrot_a:
	s_cmpk_gt_i32 s0, 0x162b
	v_readfirstlane_b32 s10, v188
	s_cbranch_scc1 .LBB0_987
	s_lshr_b32 s101, s10, 8
	v_readlane_b32 s1, v249, 0
	s_cmpk_lg_i32 s96, 0x100
	s_cbranch_scc1 .Lrot_b
	s_and_b32 s99, s1, 7
	s_lshr_b32 s1, s1, 3
	s_sub_u32 s1, s1, 1
	s_and_b32 s1, s1, 31
	s_and_b32 s100, s1, 7
	s_lshl_b32 s100, s100, 2
	s_lshr_b32 s1, s1, 3
	s_or_b32 s1, s1, s100
	s_lshl_b32 s1, s1, 3
	s_or_b32 s1, s1, s99

.LBB0_980:
	ds_read_b128 v[144:147], v151
	ds_read_b128 v[156:159], v151 offset:1024
	ds_read_b128 v[160:163], v151 offset:2048
	ds_read_b128 v[164:167], v151 offset:3072
	s_add_u32 s34, s22, 0xfffc0080
	s_addc_u32 s35, s23, -1
	s_cmp_eq_u32 s55, 12
	s_cselect_b32 s37, s15, s35
	s_cselect_b32 s36, s51, s34
	s_cselect_b32 s35, s13, s54
	s_cselect_b32 s34, s52, s53
	v_lshl_add_u64 v[218:219], s[22:23], 0, v[136:137]
	s_add_i32 m0, s21, 0xc000
	ds_read_b128 v[184:187], v153
	ds_read_b128 v[190:193], v153 offset:1024
	ds_read_b128 v[194:197], v153 offset:2048
	ds_read_b128 v[198:201], v153 offset:3072
	ds_read_b128 v[202:205], v153 offset:4096
	ds_read_b128 v[206:209], v153 offset:5120
	ds_read_b128 v[210:213], v153 offset:6144
	ds_read_b128 v[214:217], v153 offset:7168
	ds_read_b128 v[168:171], v152
	ds_read_b128 v[172:175], v152 offset:1024
	ds_read_b128 v[176:179], v152 offset:2048
	s_waitcnt lgkmcnt(14)
	ds_read_b128 v[180:183], v152 offset:3072
	global_load_lds_dwordx4 v[218:219], off
	v_lshl_add_u64 v[218:219], s[22:23], 0, v[138:139]
	s_add_i32 m0, s21, 0xe000
	s_nop 0
	global_load_lds_dwordx4 v[218:219], off
	s_waitcnt vmcnt(8)
	s_waitcnt lgkmcnt(4)
	s_cmp_eq_u32 s101, 0
	s_cbranch_scc1 .Lrx_g3_0
	s_waitcnt lgkmcnt(0)
.Lrx_g3_0:
	s_barrier
	s_setprio 1
	s_waitcnt lgkmcnt(4)
	v_mfma_f32_16x16x32_bf16 v[116:119], v[144:147], v[184:187], v[116:119]
	v_mfma_f32_16x16x32_bf16 v[112:115], v[160:163], v[184:187], v[112:115]
	v_mfma_f32_16x16x32_bf16 v[104:107], v[144:147], v[194:197], v[104:107]
	v_mfma_f32_16x16x32_bf16 v[96:99], v[160:163], v[194:197], v[96:99]
	v_mfma_f32_16x16x32_bf16 v[88:91], v[144:147], v[202:205], v[88:91]
	v_mfma_f32_16x16x32_bf16 v[80:83], v[160:163], v[202:205], v[80:83]
	v_mfma_f32_16x16x32_bf16 v[72:75], v[144:147], v[210:213], v[72:75]
	v_mfma_f32_16x16x32_bf16 v[68:71], v[160:163], v[210:213], v[68:71]
	v_mfma_f32_16x16x32_bf16 v[116:119], v[156:159], v[190:193], v[116:119]
	v_mfma_f32_16x16x32_bf16 v[112:115], v[164:167], v[190:193], v[112:115]
	v_mfma_f32_16x16x32_bf16 v[104:107], v[156:159], v[198:201], v[104:107]
	v_mfma_f32_16x16x32_bf16 v[96:99], v[164:167], v[198:201], v[96:99]
	v_mfma_f32_16x16x32_bf16 v[88:91], v[156:159], v[206:209], v[88:91]
	v_mfma_f32_16x16x32_bf16 v[80:83], v[164:167], v[206:209], v[80:83]
	v_mfma_f32_16x16x32_bf16 v[72:75], v[156:159], v[214:217], v[72:75]
	v_mfma_f32_16x16x32_bf16 v[68:71], v[164:167], v[214:217], v[68:71]
	s_setprio 0
	s_setprio 1
	s_waitcnt lgkmcnt(0)
	v_mfma_f32_16x16x32_bf16 v[124:127], v[168:171], v[184:187], v[124:127]
	v_mfma_f32_16x16x32_bf16 v[120:123], v[176:179], v[184:187], v[120:123]
	v_mfma_f32_16x16x32_bf16 v[108:111], v[168:171], v[194:197], v[108:111]
	v_mfma_f32_16x16x32_bf16 v[100:103], v[176:179], v[194:197], v[100:103]
	v_mfma_f32_16x16x32_bf16 v[92:95], v[168:171], v[202:205], v[92:95]
	v_mfma_f32_16x16x32_bf16 v[84:87], v[176:179], v[202:205], v[84:87]
	v_mfma_f32_16x16x32_bf16 v[76:79], v[168:171], v[210:213], v[76:79]
	v_mfma_f32_16x16x32_bf16 v[64:67], v[176:179], v[210:213], v[64:67]
	v_mfma_f32_16x16x32_bf16 v[124:127], v[172:175], v[190:193], v[124:127]
	v_mfma_f32_16x16x32_bf16 v[120:123], v[180:183], v[190:193], v[120:123]
	v_mfma_f32_16x16x32_bf16 v[108:111], v[172:175], v[198:201], v[108:111]
	v_mfma_f32_16x16x32_bf16 v[100:103], v[180:183], v[198:201], v[100:103]
	v_mfma_f32_16x16x32_bf16 v[92:95], v[172:175], v[206:209], v[92:95]
	v_mfma_f32_16x16x32_bf16 v[84:87], v[180:183], v[206:209], v[84:87]
	v_mfma_f32_16x16x32_bf16 v[76:79], v[172:175], v[214:217], v[76:79]
	v_mfma_f32_16x16x32_bf16 v[64:67], v[180:183], v[214:217], v[64:67]
	s_setprio 0
	s_barrier
	s_add_i32 s56, s47, s38
	v_lshl_add_u64 v[218:219], s[34:35], 0, v[130:131]
	s_mov_b32 m0, s56
	ds_read_b128 v[184:187], v153 offset:16384
	ds_read_b128 v[190:193], v153 offset:17408
	ds_read_b128 v[194:197], v153 offset:18432
	ds_read_b128 v[198:201], v153 offset:19456
	ds_read_b128 v[202:205], v153 offset:20480
	ds_read_b128 v[206:209], v153 offset:21504
	ds_read_b128 v[210:213], v153 offset:22528
	ds_read_b128 v[214:217], v153 offset:23552
	global_load_lds_dwordx4 v[218:219], off
	s_add_i32 m0, s56, 0x2000
	s_add_u32 s56, s34, 0x40000
	v_lshl_add_u64 v[220:221], s[34:35], 0, v[134:135]
	s_addc_u32 s57, s35, 0
	s_add_i32 s58, s48, s38
	global_load_lds_dwordx4 v[220:221], off
	v_lshl_add_u64 v[222:223], s[56:57], 0, v[130:131]
	s_mov_b32 m0, s58
	v_lshl_add_u64 v[224:225], s[36:37], 0, v[132:133]
	global_load_lds_dwordx4 v[222:223], off
	v_lshl_add_u64 v[222:223], s[56:57], 0, v[134:135]
	s_add_i32 m0, s58, 0x2000
	s_nop 0
	global_load_lds_dwordx4 v[222:223], off
	v_lshl_add_u64 v[222:223], s[36:37], 0, v[128:129]
	s_mov_b32 m0, s21
	s_nop 0
	global_load_lds_dwordx4 v[222:223], off
	s_mov_b32 m0, s39
	s_nop 0
	global_load_lds_dwordx4 v[224:225], off
	s_waitcnt vmcnt(8)
	s_waitcnt lgkmcnt(0)
	s_barrier
	s_setprio 1
	s_waitcnt lgkmcnt(0)
	v_mfma_f32_16x16x32_bf16 v[56:59], v[144:147], v[184:187], v[56:59]
	v_mfma_f32_16x16x32_bf16 v[48:51], v[160:163], v[184:187], v[48:51]
	v_mfma_f32_16x16x32_bf16 v[40:43], v[144:147], v[194:197], v[40:43]
	v_mfma_f32_16x16x32_bf16 v[32:35], v[160:163], v[194:197], v[32:35]
	v_mfma_f32_16x16x32_bf16 v[24:27], v[144:147], v[202:205], v[24:27]
	v_mfma_f32_16x16x32_bf16 v[16:19], v[160:163], v[202:205], v[16:19]
	v_mfma_f32_16x16x32_bf16 v[8:11], v[144:147], v[210:213], v[8:11]
	v_mfma_f32_16x16x32_bf16 v[0:3], v[160:163], v[210:213], v[0:3]
	v_mfma_f32_16x16x32_bf16 v[56:59], v[156:159], v[190:193], v[56:59]
	v_mfma_f32_16x16x32_bf16 v[48:51], v[164:167], v[190:193], v[48:51]
	v_mfma_f32_16x16x32_bf16 v[40:43], v[156:159], v[198:201], v[40:43]
	v_mfma_f32_16x16x32_bf16 v[32:35], v[164:167], v[198:201], v[32:35]
	v_mfma_f32_16x16x32_bf16 v[24:27], v[156:159], v[206:209], v[24:27]
	v_mfma_f32_16x16x32_bf16 v[16:19], v[164:167], v[206:209], v[16:19]
	v_mfma_f32_16x16x32_bf16 v[8:11], v[156:159], v[214:217], v[8:11]
	v_mfma_f32_16x16x32_bf16 v[0:3], v[164:167], v[214:217], v[0:3]
	s_setprio 0
	s_setprio 1
	v_mfma_f32_16x16x32_bf16 v[60:63], v[168:171], v[184:187], v[60:63]
	v_mfma_f32_16x16x32_bf16 v[52:55], v[176:179], v[184:187], v[52:55]
	v_mfma_f32_16x16x32_bf16 v[44:47], v[168:171], v[194:197], v[44:47]
	v_mfma_f32_16x16x32_bf16 v[36:39], v[176:179], v[194:197], v[36:39]
	v_mfma_f32_16x16x32_bf16 v[28:31], v[168:171], v[202:205], v[28:31]
	v_mfma_f32_16x16x32_bf16 v[20:23], v[176:179], v[202:205], v[20:23]
	v_mfma_f32_16x16x32_bf16 v[12:15], v[168:171], v[210:213], v[12:15]
	v_mfma_f32_16x16x32_bf16 v[4:7], v[176:179], v[210:213], v[4:7]
	v_mfma_f32_16x16x32_bf16 v[60:63], v[172:175], v[190:193], v[60:63]
	v_mfma_f32_16x16x32_bf16 v[52:55], v[180:183], v[190:193], v[52:55]
	v_mfma_f32_16x16x32_bf16 v[44:47], v[172:175], v[198:201], v[44:47]
	v_mfma_f32_16x16x32_bf16 v[36:39], v[180:183], v[198:201], v[36:39]
	v_mfma_f32_16x16x32_bf16 v[28:31], v[172:175], v[206:209], v[28:31]
	v_mfma_f32_16x16x32_bf16 v[20:23], v[180:183], v[206:209], v[20:23]
	v_mfma_f32_16x16x32_bf16 v[12:15], v[172:175], v[214:217], v[12:15]
	v_mfma_f32_16x16x32_bf16 v[4:7], v[180:183], v[214:217], v[4:7]
	s_setprio 0
	s_barrier
	s_add_i32 s56, 0, 0x18000
	v_add_u32_e32 v155, s56, v149
	s_add_i32 s57, 0, 0x1c000
	ds_read_b128 v[144:147], v155
	ds_read_b128 v[156:159], v155 offset:1024
	ds_read_b128 v[160:163], v155 offset:2048
	ds_read_b128 v[164:167], v155 offset:3072
	s_add_u32 s36, s36, 0x40000
	s_addc_u32 s37, s37, 0
	s_mov_b32 m0, s40
	v_lshl_add_u64 v[226:227], s[36:37], 0, v[128:129]
	ds_read_b128 v[184:187], v153 offset:32768
	ds_read_b128 v[190:193], v153 offset:33792
	ds_read_b128 v[194:197], v153 offset:34816
	ds_read_b128 v[198:201], v153 offset:35840
	ds_read_b128 v[202:205], v153 offset:36864
	ds_read_b128 v[206:209], v153 offset:37888
	ds_read_b128 v[210:213], v153 offset:38912
	ds_read_b128 v[214:217], v153 offset:39936
	v_add_u32_e32 v155, s57, v149
	ds_read_b128 v[168:171], v155
	ds_read_b128 v[172:175], v155 offset:1024
	ds_read_b128 v[176:179], v155 offset:2048
	s_waitcnt lgkmcnt(14)
	ds_read_b128 v[180:183], v155 offset:3072
	global_load_lds_dwordx4 v[226:227], off
	v_lshl_add_u64 v[226:227], s[36:37], 0, v[132:133]
	s_mov_b32 m0, s41
	s_nop 0
	global_load_lds_dwordx4 v[226:227], off
	s_waitcnt vmcnt(8)
	s_waitcnt lgkmcnt(4)
	s_cmp_eq_u32 s101, 0
	s_cbranch_scc1 .Lrx_g3_1
	s_waitcnt lgkmcnt(0)
.Lrx_g3_1:
	s_barrier
	s_setprio 1
	s_waitcnt lgkmcnt(4)
	v_mfma_f32_16x16x32_bf16 v[116:119], v[144:147], v[184:187], v[116:119]
	v_mfma_f32_16x16x32_bf16 v[112:115], v[160:163], v[184:187], v[112:115]
	v_mfma_f32_16x16x32_bf16 v[104:107], v[144:147], v[194:197], v[104:107]
	v_mfma_f32_16x16x32_bf16 v[96:99], v[160:163], v[194:197], v[96:99]
	v_mfma_f32_16x16x32_bf16 v[88:91], v[144:147], v[202:205], v[88:91]
	v_mfma_f32_16x16x32_bf16 v[80:83], v[160:163], v[202:205], v[80:83]
	v_mfma_f32_16x16x32_bf16 v[72:75], v[144:147], v[210:213], v[72:75]
	v_mfma_f32_16x16x32_bf16 v[68:71], v[160:163], v[210:213], v[68:71]
	v_mfma_f32_16x16x32_bf16 v[116:119], v[156:159], v[190:193], v[116:119]
	v_mfma_f32_16x16x32_bf16 v[112:115], v[164:167], v[190:193], v[112:115]
	v_mfma_f32_16x16x32_bf16 v[104:107], v[156:159], v[198:201], v[104:107]
	v_mfma_f32_16x16x32_bf16 v[96:99], v[164:167], v[198:201], v[96:99]
	v_mfma_f32_16x16x32_bf16 v[88:91], v[156:159], v[206:209], v[88:91]
	v_mfma_f32_16x16x32_bf16 v[80:83], v[164:167], v[206:209], v[80:83]
	v_mfma_f32_16x16x32_bf16 v[72:75], v[156:159], v[214:217], v[72:75]
	v_mfma_f32_16x16x32_bf16 v[68:71], v[164:167], v[214:217], v[68:71]
	s_setprio 0
	s_setprio 1
	s_waitcnt lgkmcnt(0)
	v_mfma_f32_16x16x32_bf16 v[124:127], v[168:171], v[184:187], v[124:127]
	v_mfma_f32_16x16x32_bf16 v[120:123], v[176:179], v[184:187], v[120:123]
	v_mfma_f32_16x16x32_bf16 v[108:111], v[168:171], v[194:197], v[108:111]
	v_mfma_f32_16x16x32_bf16 v[100:103], v[176:179], v[194:197], v[100:103]
	v_mfma_f32_16x16x32_bf16 v[92:95], v[168:171], v[202:205], v[92:95]
	v_mfma_f32_16x16x32_bf16 v[84:87], v[176:179], v[202:205], v[84:87]
	v_mfma_f32_16x16x32_bf16 v[76:79], v[168:171], v[210:213], v[76:79]
	v_mfma_f32_16x16x32_bf16 v[64:67], v[176:179], v[210:213], v[64:67]
	v_mfma_f32_16x16x32_bf16 v[124:127], v[172:175], v[190:193], v[124:127]
	v_mfma_f32_16x16x32_bf16 v[120:123], v[180:183], v[190:193], v[120:123]
	v_mfma_f32_16x16x32_bf16 v[108:111], v[172:175], v[198:201], v[108:111]
	v_mfma_f32_16x16x32_bf16 v[100:103], v[180:183], v[198:201], v[100:103]
	v_mfma_f32_16x16x32_bf16 v[92:95], v[172:175], v[206:209], v[92:95]
	v_mfma_f32_16x16x32_bf16 v[84:87], v[180:183], v[206:209], v[84:87]
	v_mfma_f32_16x16x32_bf16 v[76:79], v[172:175], v[214:217], v[76:79]
	v_mfma_f32_16x16x32_bf16 v[64:67], v[180:183], v[214:217], v[64:67]
	s_setprio 0
	s_barrier
	s_add_i32 s36, s56, s38
	v_lshl_add_u64 v[218:219], v[218:219], 0, s[8:9]
	s_mov_b32 m0, s36
	ds_read_b128 v[184:187], v153 offset:49152
	ds_read_b128 v[190:193], v153 offset:50176
	ds_read_b128 v[194:197], v153 offset:51200
	ds_read_b128 v[198:201], v153 offset:52224
	ds_read_b128 v[202:205], v153 offset:53248
	ds_read_b128 v[206:209], v153 offset:54272
	ds_read_b128 v[210:213], v153 offset:55296
	ds_read_b128 v[214:217], v153 offset:56320
	global_load_lds_dwordx4 v[218:219], off
	s_add_i32 m0, s36, 0x2000
	s_add_u32 s34, s34, 0x40080
	v_lshl_add_u64 v[218:219], v[220:221], 0, s[8:9]
	s_addc_u32 s35, s35, 0
	s_add_i32 s36, s57, s38
	global_load_lds_dwordx4 v[218:219], off
	v_lshl_add_u64 v[218:219], s[34:35], 0, v[130:131]
	s_mov_b32 m0, s36
	s_nop 0
	global_load_lds_dwordx4 v[218:219], off
	v_lshl_add_u64 v[218:219], s[34:35], 0, v[134:135]
	s_add_i32 m0, s36, 0x2000
	s_nop 0
	global_load_lds_dwordx4 v[218:219], off
	v_lshl_add_u64 v[218:219], v[222:223], 0, s[8:9]
	s_mov_b32 m0, s43
	s_nop 0
	global_load_lds_dwordx4 v[218:219], off
	v_lshl_add_u64 v[218:219], v[224:225], 0, s[8:9]
	s_mov_b32 m0, s44
	s_nop 0
	global_load_lds_dwordx4 v[218:219], off
	s_waitcnt vmcnt(8)
	s_waitcnt lgkmcnt(0)
	s_barrier
	s_setprio 1
	s_waitcnt lgkmcnt(0)
	v_mfma_f32_16x16x32_bf16 v[56:59], v[144:147], v[184:187], v[56:59]
	v_mfma_f32_16x16x32_bf16 v[48:51], v[160:163], v[184:187], v[48:51]
	v_mfma_f32_16x16x32_bf16 v[40:43], v[144:147], v[194:197], v[40:43]
	v_mfma_f32_16x16x32_bf16 v[32:35], v[160:163], v[194:197], v[32:35]
	v_mfma_f32_16x16x32_bf16 v[24:27], v[144:147], v[202:205], v[24:27]
	v_mfma_f32_16x16x32_bf16 v[16:19], v[160:163], v[202:205], v[16:19]
	v_mfma_f32_16x16x32_bf16 v[8:11], v[144:147], v[210:213], v[8:11]
	v_mfma_f32_16x16x32_bf16 v[0:3], v[160:163], v[210:213], v[0:3]
	v_mfma_f32_16x16x32_bf16 v[56:59], v[156:159], v[190:193], v[56:59]
	v_mfma_f32_16x16x32_bf16 v[48:51], v[164:167], v[190:193], v[48:51]
	v_mfma_f32_16x16x32_bf16 v[40:43], v[156:159], v[198:201], v[40:43]
	v_mfma_f32_16x16x32_bf16 v[32:35], v[164:167], v[198:201], v[32:35]
	v_mfma_f32_16x16x32_bf16 v[24:27], v[156:159], v[206:209], v[24:27]
	v_mfma_f32_16x16x32_bf16 v[16:19], v[164:167], v[206:209], v[16:19]
	v_mfma_f32_16x16x32_bf16 v[8:11], v[156:159], v[214:217], v[8:11]
	v_mfma_f32_16x16x32_bf16 v[0:3], v[164:167], v[214:217], v[0:3]
	s_setprio 0
	s_setprio 1
	v_mfma_f32_16x16x32_bf16 v[60:63], v[168:171], v[184:187], v[60:63]
	v_mfma_f32_16x16x32_bf16 v[52:55], v[176:179], v[184:187], v[52:55]
	v_mfma_f32_16x16x32_bf16 v[44:47], v[168:171], v[194:197], v[44:47]
	v_mfma_f32_16x16x32_bf16 v[36:39], v[176:179], v[194:197], v[36:39]
	v_mfma_f32_16x16x32_bf16 v[28:31], v[168:171], v[202:205], v[28:31]
	v_mfma_f32_16x16x32_bf16 v[20:23], v[176:179], v[202:205], v[20:23]
	v_mfma_f32_16x16x32_bf16 v[12:15], v[168:171], v[210:213], v[12:15]
	v_mfma_f32_16x16x32_bf16 v[4:7], v[176:179], v[210:213], v[4:7]
	v_mfma_f32_16x16x32_bf16 v[60:63], v[172:175], v[190:193], v[60:63]
	v_mfma_f32_16x16x32_bf16 v[52:55], v[180:183], v[190:193], v[52:55]
	v_mfma_f32_16x16x32_bf16 v[44:47], v[172:175], v[198:201], v[44:47]
	v_mfma_f32_16x16x32_bf16 v[36:39], v[180:183], v[198:201], v[36:39]
	v_mfma_f32_16x16x32_bf16 v[28:31], v[172:175], v[206:209], v[28:31]
	v_mfma_f32_16x16x32_bf16 v[20:23], v[180:183], v[206:209], v[20:23]
	v_mfma_f32_16x16x32_bf16 v[12:15], v[172:175], v[214:217], v[12:15]
	v_mfma_f32_16x16x32_bf16 v[4:7], v[180:183], v[214:217], v[4:7]
	s_setprio 0
	s_barrier
	s_add_i32 s55, s55, 2
	s_add_u32 s22, s22, 0x100
	s_addc_u32 s23, s23, 0
	s_add_u32 s53, s53, 0x100
	s_addc_u32 s54, s54, 0
	s_cmp_gt_u32 s55, 13
	s_cbranch_scc0 .LBB0_980
	v_lshl_add_u32 v236, s20, 8, v148
	v_lshlrev_b32_e32 v236, 2, v236
	global_load_dword v228, v236, s[6:7]
	global_load_dword v229, v236, s[6:7] offset:64
	global_load_dword v230, v236, s[6:7] offset:128
	global_load_dword v231, v236, s[6:7] offset:192
	global_load_dword v232, v236, s[6:7] offset:512
	global_load_dword v233, v236, s[6:7] offset:576
	global_load_dword v234, v236, s[6:7] offset:640
	global_load_dword v235, v236, s[6:7] offset:704
	s_and_b64 vcc, exec, s[10:11]
	s_cbranch_vccz .LBB0_983
	s_barrier
